# v63: placement check compares workgroups of one bid&7 group with each other (XCD ids are a permutation on this device); L2 write-back before hand-offs only if a group is split
# speedup vs baseline: 1.0140x; 1.0111x over previous
.LBB0_9:
	s_mul_i32 s3, s6, 3
	s_getpc_b64 s[0:1]
	s_add_u32 s0, s0, PROG@rel32@lo+4
	s_addc_u32 s1, s1, PROG@rel32@hi+12
	s_and_b32 s2, s3, -4
	s_add_u32 s0, s0, s2
	s_addc_u32 s1, s1, 0
	s_load_dwordx2 s[0:1], s[0:1], 0x0
	s_and_b32 s3, s3, 3
	s_lshl_b32 s3, s3, 3
	s_waitcnt lgkmcnt(0)
	s_lshr_b64 s[0:1], s[0:1], s3
	s_and_b32 s2, s0, 0xffff
	v_mov_b32_e32 v0, s2
	s_bfe_u32 s2, s0, 0x80010
	v_mov_b32_e32 v2, s2
	s_cmp_gt_u32 s6, 1
	s_cbranch_scc1 .Lsm_done
	v_readlane_b32 s0, v254, 39
	v_readlane_b32 s1, v254, 40
	s_add_u32 s0, s0, 0xc000
	s_addc_u32 s1, s1, 0
	s_cmp_eq_u32 s6, 1
	s_cbranch_scc1 .Lsm_cache
	s_getreg_b32 s2, hwreg(HW_REG_XCC_ID, 0, 4)
	s_and_b32 s2, s2, 15
	s_lshl_b32 s2, 1, s2
	s_and_b32 s3, s66, 7
	s_lshl_b32 s3, s3, 2
	s_add_u32 s0, s0, s3
	s_addc_u32 s1, s1, 0
	v_mov_b32_e32 v3, s2
	s_mov_b64 s[2:3], exec
	s_mov_b64 exec, 1
	global_atomic_or v1, v3, s[0:1]
	s_mov_b64 exec, s[2:3]
	s_branch .Lsm_done
	s_nop 0
	s_nop 0
	s_nop 0
	s_nop 0
	s_nop 0
	s_nop 0
.Lsm_cache:
	global_load_dwordx4 v[4:7], v1, s[0:1] sc1
	global_load_dwordx4 v[8:11], v1, s[0:1] offset:16 sc1
	s_waitcnt vmcnt(0)
	v_add_u32_e32 v3, -1, v4
	v_and_b32_e32 v3, v3, v4
	v_add_u32_e32 v4, -1, v5
	v_and_or_b32 v3, v4, v5, v3
	v_add_u32_e32 v4, -1, v6
	v_and_or_b32 v3, v4, v6, v3
	v_add_u32_e32 v4, -1, v7
	v_and_or_b32 v3, v4, v7, v3
	v_add_u32_e32 v4, -1, v8
	v_and_or_b32 v3, v4, v8, v3
	v_add_u32_e32 v4, -1, v9
	v_and_or_b32 v3, v4, v9, v3
	v_add_u32_e32 v4, -1, v10
	v_and_or_b32 v3, v4, v10, v3
	v_add_u32_e32 v4, -1, v11
	v_and_or_b32 v3, v4, v11, v3
	s_nop 0
	v_readfirstlane_b32 s2, v3
	s_nop 1
	v_writelane_b32 v255, s2, 63
